# s8p + leading half issues its G1/G3 epilogue operand loads before the unit-end barrier
# speedup vs baseline: 1.0063x; 1.0028x over previous
.Lmy_sk2:
	s_waitcnt lgkmcnt(0)
	s_setprio 1
	s_barrier
	v_mfma_f32_16x16x32_bf16 v[62:65], v[132:135], v[184:187], v[62:65]
	v_mfma_f32_16x16x32_bf16 v[58:61], v[140:143], v[184:187], v[58:61]
	v_mfma_f32_16x16x32_bf16 v[54:57], v[132:135], v[192:195], v[54:57]
	v_mfma_f32_16x16x32_bf16 v[46:49], v[140:143], v[192:195], v[46:49]
	v_mfma_f32_16x16x32_bf16 v[38:41], v[132:135], v[208:211], v[38:41]
	v_mfma_f32_16x16x32_bf16 v[30:33], v[140:143], v[208:211], v[30:33]
	v_mfma_f32_16x16x32_bf16 v[22:25], v[132:135], v[216:219], v[22:25]
	v_mfma_f32_16x16x32_bf16 v[14:17], v[140:143], v[216:219], v[14:17]
	v_mfma_f32_16x16x32_bf16 v[62:65], v[136:139], v[188:191], v[62:65]
	v_mfma_f32_16x16x32_bf16 v[58:61], v[144:147], v[188:191], v[58:61]
	v_mfma_f32_16x16x32_bf16 v[54:57], v[136:139], v[204:207], v[54:57]
	v_mfma_f32_16x16x32_bf16 v[46:49], v[144:147], v[204:207], v[46:49]
	v_mfma_f32_16x16x32_bf16 v[38:41], v[136:139], v[212:215], v[38:41]
	v_mfma_f32_16x16x32_bf16 v[30:33], v[144:147], v[212:215], v[30:33]
	v_mfma_f32_16x16x32_bf16 v[22:25], v[136:139], v[220:223], v[22:25]
	v_mfma_f32_16x16x32_bf16 v[14:17], v[144:147], v[220:223], v[14:17]
	s_setprio 0
	s_setprio 1
	v_mfma_f32_16x16x32_bf16 v[50:53], v[156:159], v[184:187], v[50:53]
	v_mfma_f32_16x16x32_bf16 v[42:45], v[164:167], v[184:187], v[42:45]
	v_mfma_f32_16x16x32_bf16 v[34:37], v[156:159], v[192:195], v[34:37]
	v_mfma_f32_16x16x32_bf16 v[26:29], v[164:167], v[192:195], v[26:29]
	v_mfma_f32_16x16x32_bf16 v[18:21], v[156:159], v[208:211], v[18:21]
	v_mfma_f32_16x16x32_bf16 v[10:13], v[164:167], v[208:211], v[10:13]
	v_mfma_f32_16x16x32_bf16 v[6:9], v[156:159], v[216:219], v[6:9]
	v_mfma_f32_16x16x32_bf16 v[2:5], v[164:167], v[216:219], v[2:5]
	v_mfma_f32_16x16x32_bf16 v[50:53], v[160:163], v[188:191], v[50:53]
	v_mfma_f32_16x16x32_bf16 v[42:45], v[180:183], v[188:191], v[42:45]
	v_mfma_f32_16x16x32_bf16 v[34:37], v[160:163], v[204:207], v[34:37]
	v_mfma_f32_16x16x32_bf16 v[26:29], v[180:183], v[204:207], v[26:29]
	v_mfma_f32_16x16x32_bf16 v[18:21], v[160:163], v[212:215], v[18:21]
	v_mfma_f32_16x16x32_bf16 v[10:13], v[180:183], v[212:215], v[10:13]
	v_mfma_f32_16x16x32_bf16 v[6:9], v[160:163], v[220:223], v[6:9]
	v_mfma_f32_16x16x32_bf16 v[2:5], v[180:183], v[220:223], v[2:5]
	s_setprio 0
	s_barrier
	s_add_i32 s4, 0, 0x18000
	s_add_i32 s5, 0, 0x1c000
	v_add_u32_e32 v144, s4, v175
	v_add_u32_e32 v170, s5, v175
	ds_read_b128 v[132:135], v144
	ds_read_b128 v[136:139], v144 offset:1024
	ds_read_b128 v[140:143], v144 offset:2048
	ds_read_b128 v[144:147], v144 offset:3072
	ds_read_b128 v[156:159], v170
	ds_read_b128 v[160:163], v170 offset:1024
	ds_read_b128 v[164:167], v170 offset:2048
	ds_read_b128 v[180:183], v170 offset:3072
	s_add_u32 s44, s70, 0x40000
	s_addc_u32 s45, s71, 0
	v_lshl_add_u64 v[202:203], s[44:45], 0, v[98:99]
	s_add_i32 m0, s94, 0x4000
	ds_read_b128 v[184:187], v179 offset:32768
	ds_read_b128 v[188:191], v179 offset:33792
	ds_read_b128 v[192:195], v179 offset:34816
	ds_read_b128 v[204:207], v179 offset:35840
	ds_read_b128 v[208:211], v179 offset:36864
	ds_read_b128 v[212:215], v179 offset:37888
	ds_read_b128 v[216:219], v179 offset:38912
	ds_read_b128 v[220:223], v179 offset:39936
	global_load_lds_dwordx4 v[202:203], off
	v_lshl_add_u64 v[202:203], s[44:45], 0, v[150:151]
	s_add_i32 m0, s94, 0x6000
	s_nop 0
	global_load_lds_dwordx4 v[202:203], off
	s_waitcnt vmcnt(8)
	s_waitcnt lgkmcnt(0)
	s_setprio 1
	s_barrier
	v_mfma_f32_16x16x32_bf16 v[128:131], v[132:135], v[184:187], v[128:131]
	v_mfma_f32_16x16x32_bf16 v[124:127], v[140:143], v[184:187], v[124:127]
	v_mfma_f32_16x16x32_bf16 v[120:123], v[132:135], v[192:195], v[120:123]
	v_mfma_f32_16x16x32_bf16 v[112:115], v[140:143], v[192:195], v[112:115]
	v_mfma_f32_16x16x32_bf16 v[104:107], v[132:135], v[208:211], v[104:107]
	v_mfma_f32_16x16x32_bf16 v[94:97], v[140:143], v[208:211], v[94:97]
	v_mfma_f32_16x16x32_bf16 v[86:89], v[132:135], v[216:219], v[86:89]
	v_mfma_f32_16x16x32_bf16 v[78:81], v[140:143], v[216:219], v[78:81]
	v_mfma_f32_16x16x32_bf16 v[128:131], v[136:139], v[188:191], v[128:131]
	v_mfma_f32_16x16x32_bf16 v[124:127], v[144:147], v[188:191], v[124:127]
	v_mfma_f32_16x16x32_bf16 v[120:123], v[136:139], v[204:207], v[120:123]
	v_mfma_f32_16x16x32_bf16 v[112:115], v[144:147], v[204:207], v[112:115]
	v_mfma_f32_16x16x32_bf16 v[104:107], v[136:139], v[212:215], v[104:107]
	v_mfma_f32_16x16x32_bf16 v[94:97], v[144:147], v[212:215], v[94:97]
	v_mfma_f32_16x16x32_bf16 v[86:89], v[136:139], v[220:223], v[86:89]
	v_mfma_f32_16x16x32_bf16 v[78:81], v[144:147], v[220:223], v[78:81]
	s_setprio 0
	s_setprio 1
	v_mfma_f32_16x16x32_bf16 v[116:119], v[156:159], v[184:187], v[116:119]
	v_mfma_f32_16x16x32_bf16 v[108:111], v[164:167], v[184:187], v[108:111]
	v_mfma_f32_16x16x32_bf16 v[100:103], v[156:159], v[192:195], v[100:103]
	v_mfma_f32_16x16x32_bf16 v[90:93], v[164:167], v[192:195], v[90:93]
	v_mfma_f32_16x16x32_bf16 v[82:85], v[156:159], v[208:211], v[82:85]
	v_mfma_f32_16x16x32_bf16 v[74:77], v[164:167], v[208:211], v[74:77]
	v_mfma_f32_16x16x32_bf16 v[70:73], v[156:159], v[216:219], v[70:73]
	v_mfma_f32_16x16x32_bf16 v[66:69], v[164:167], v[216:219], v[66:69]
	v_mfma_f32_16x16x32_bf16 v[116:119], v[160:163], v[188:191], v[116:119]
	v_mfma_f32_16x16x32_bf16 v[108:111], v[180:183], v[188:191], v[108:111]
	v_mfma_f32_16x16x32_bf16 v[100:103], v[160:163], v[204:207], v[100:103]
	v_mfma_f32_16x16x32_bf16 v[90:93], v[180:183], v[204:207], v[90:93]
	v_mfma_f32_16x16x32_bf16 v[82:85], v[160:163], v[212:215], v[82:85]
	v_mfma_f32_16x16x32_bf16 v[74:77], v[180:183], v[212:215], v[74:77]
	v_mfma_f32_16x16x32_bf16 v[70:73], v[160:163], v[220:223], v[70:73]
	v_mfma_f32_16x16x32_bf16 v[66:69], v[180:183], v[220:223], v[66:69]
	s_setprio 0
	s_barrier
	s_add_i32 s4, s4, s77
	v_lshl_add_u64 v[168:169], v[168:169], 0, s[42:43]
	s_mov_b32 m0, s4
	ds_read_b128 v[184:187], v179 offset:49152
	ds_read_b128 v[188:191], v179 offset:50176
	ds_read_b128 v[192:195], v179 offset:51200
	ds_read_b128 v[204:207], v179 offset:52224
	ds_read_b128 v[208:211], v179 offset:53248
	ds_read_b128 v[212:215], v179 offset:54272
	ds_read_b128 v[216:219], v179 offset:55296
	ds_read_b128 v[220:223], v179 offset:56320
	global_load_lds_dwordx4 v[168:169], off
	s_add_i32 m0, s4, 0x2000
	s_add_u32 s44, s68, 0x40080
	v_lshl_add_u64 v[168:169], v[172:173], 0, s[42:43]
	s_addc_u32 s45, s69, 0
	s_add_i32 s4, s5, s77
	global_load_lds_dwordx4 v[168:169], off
	v_lshl_add_u64 v[168:169], s[44:45], 0, v[148:149]
	s_mov_b32 m0, s4
	s_nop 0
	global_load_lds_dwordx4 v[168:169], off
	v_lshl_add_u64 v[168:169], s[44:45], 0, v[152:153]
	s_add_i32 m0, s4, 0x2000
	s_nop 0
	global_load_lds_dwordx4 v[168:169], off
	v_lshl_add_u64 v[168:169], v[176:177], 0, s[42:43]
	s_add_i32 m0, s94, 0x8000
	s_nop 0
	global_load_lds_dwordx4 v[168:169], off
	v_lshl_add_u64 v[168:169], v[200:201], 0, s[42:43]
	s_add_i32 m0, s94, 0xa000
	s_nop 0
	global_load_lds_dwordx4 v[168:169], off
	s_waitcnt vmcnt(8)
	s_waitcnt lgkmcnt(0)
	s_setprio 1
	s_barrier
	v_mfma_f32_16x16x32_bf16 v[62:65], v[132:135], v[184:187], v[62:65]
	v_mfma_f32_16x16x32_bf16 v[58:61], v[140:143], v[184:187], v[58:61]
	v_mfma_f32_16x16x32_bf16 v[54:57], v[132:135], v[192:195], v[54:57]
	v_mfma_f32_16x16x32_bf16 v[46:49], v[140:143], v[192:195], v[46:49]
	v_mfma_f32_16x16x32_bf16 v[38:41], v[132:135], v[208:211], v[38:41]
	v_mfma_f32_16x16x32_bf16 v[30:33], v[140:143], v[208:211], v[30:33]
	v_mfma_f32_16x16x32_bf16 v[22:25], v[132:135], v[216:219], v[22:25]
	v_mfma_f32_16x16x32_bf16 v[14:17], v[140:143], v[216:219], v[14:17]
	v_mfma_f32_16x16x32_bf16 v[62:65], v[136:139], v[188:191], v[62:65]
	v_mfma_f32_16x16x32_bf16 v[58:61], v[144:147], v[188:191], v[58:61]
	v_mfma_f32_16x16x32_bf16 v[54:57], v[136:139], v[204:207], v[54:57]
	v_mfma_f32_16x16x32_bf16 v[46:49], v[144:147], v[204:207], v[46:49]
	v_mfma_f32_16x16x32_bf16 v[38:41], v[136:139], v[212:215], v[38:41]
	v_mfma_f32_16x16x32_bf16 v[30:33], v[144:147], v[212:215], v[30:33]
	v_mfma_f32_16x16x32_bf16 v[22:25], v[136:139], v[220:223], v[22:25]
	v_mfma_f32_16x16x32_bf16 v[14:17], v[144:147], v[220:223], v[14:17]
	s_setprio 0
	s_setprio 1
	v_mfma_f32_16x16x32_bf16 v[50:53], v[156:159], v[184:187], v[50:53]
	v_mfma_f32_16x16x32_bf16 v[42:45], v[164:167], v[184:187], v[42:45]
	v_mfma_f32_16x16x32_bf16 v[34:37], v[156:159], v[192:195], v[34:37]
	v_mfma_f32_16x16x32_bf16 v[26:29], v[164:167], v[192:195], v[26:29]
	v_mfma_f32_16x16x32_bf16 v[18:21], v[156:159], v[208:211], v[18:21]
	v_mfma_f32_16x16x32_bf16 v[10:13], v[164:167], v[208:211], v[10:13]
	v_mfma_f32_16x16x32_bf16 v[6:9], v[156:159], v[216:219], v[6:9]
	v_mfma_f32_16x16x32_bf16 v[2:5], v[164:167], v[216:219], v[2:5]
	v_mfma_f32_16x16x32_bf16 v[50:53], v[160:163], v[188:191], v[50:53]
	v_mfma_f32_16x16x32_bf16 v[42:45], v[180:183], v[188:191], v[42:45]
	v_mfma_f32_16x16x32_bf16 v[34:37], v[160:163], v[204:207], v[34:37]
	v_mfma_f32_16x16x32_bf16 v[26:29], v[180:183], v[204:207], v[26:29]
	v_mfma_f32_16x16x32_bf16 v[18:21], v[160:163], v[212:215], v[18:21]
	v_mfma_f32_16x16x32_bf16 v[10:13], v[180:183], v[212:215], v[10:13]
	v_mfma_f32_16x16x32_bf16 v[6:9], v[160:163], v[220:223], v[6:9]
	v_mfma_f32_16x16x32_bf16 v[2:5], v[180:183], v[220:223], v[2:5]
	s_setprio 0
	s_barrier
	s_mov_b32 s100, 0
	s_add_i32 s93, s93, 2
	s_add_u32 s0, s0, 0x100
	s_addc_u32 s1, s1, 0
	s_add_u32 s91, s91, 0x100
	s_addc_u32 s92, s92, 0
	s_cmp_gt_u32 s93, 13
	s_cbranch_scc0 .LBB0_322
	s_mov_b32 s100, 1
	s_and_b64 vcc, exec, s[14:15]
	s_cbranch_vccz .LBB0_325
	s_lshl_b32 s0, s89, 8
	v_add_u32_e32 v176, s0, v171
	v_ashrrev_i32_e32 v177, 31, v176
	v_or_b32_e32 v172, 16, v176
	v_lshlrev_b64 v[132:133], 6, v[176:177]
	v_ashrrev_i32_e32 v173, 31, v172
	v_or_b32_e32 v168, 32, v176
	v_lshl_add_u64 v[132:133], v[154:155], 0, v[132:133]
	v_lshlrev_b64 v[134:135], 6, v[172:173]
	v_ashrrev_i32_e32 v169, 31, v168
	v_lshl_add_u64 v[134:135], v[154:155], 0, v[134:135]
	global_load_dwordx4 v[180:183], v[132:133], off
	global_load_dwordx4 v[184:187], v[134:135], off
	v_lshlrev_b64 v[132:133], 6, v[168:169]
	v_lshl_add_u64 v[132:133], v[154:155], 0, v[132:133]
	global_load_dwordx4 v[188:191], v[132:133], off
	v_or_b32_e32 v166, 48, v176
	v_ashrrev_i32_e32 v167, 31, v166
	v_lshlrev_b64 v[132:133], 6, v[166:167]
	v_lshl_add_u64 v[132:133], v[154:155], 0, v[132:133]
	global_load_dwordx4 v[192:195], v[132:133], off
	v_add_u32_e32 v162, 0x80, v176
	v_ashrrev_i32_e32 v163, 31, v162
	v_lshlrev_b64 v[132:133], 6, v[162:163]
	v_lshl_add_u64 v[132:133], v[154:155], 0, v[132:133]
	global_load_dwordx4 v[204:207], v[132:133], off
	s_addk_i32 s0, 0xc000
	s_lshr_b32 s0, s0, 12
	v_add_u32_e32 v164, 0x90, v176
	s_ashr_i32 s1, s89, 5
	v_and_b32_e32 v132, 64, v229
	v_ashrrev_i32_e32 v165, 31, v164
	s_add_i32 s0, s0, 2
	v_add_u32_e32 v136, 64, v132
	v_lshlrev_b64 v[132:133], 6, v[164:165]
	v_add_u32_e32 v160, 0xa0, v176
	s_cmp_lt_i32 s89, 64
	v_lshl_add_u64 v[132:133], v[154:155], 0, v[132:133]
	v_ashrrev_i32_e32 v161, 31, v160
	s_cselect_b32 s0, s1, s0
	v_xor_b32_e32 v134, 16, v229
	global_load_dwordx4 v[208:211], v[132:133], off
	v_add_u32_e32 v158, 0xb0, v176
	v_lshlrev_b64 v[132:133], 6, v[160:161]
	s_mul_hi_i32 s1, s0, 0x1800
	s_mulk_i32 s0, 0x1800
	v_lshl_or_b32 v156, s90, 8, v178
	v_xor_b32_e32 v135, 32, v229
	v_cmp_lt_i32_e32 vcc, v134, v136
	v_ashrrev_i32_e32 v159, 31, v158
	v_lshl_add_u64 v[132:133], v[154:155], 0, v[132:133]
	s_add_u32 s0, s78, s0
	v_ashrrev_i32_e32 v157, 31, v156
	v_cndmask_b32_e32 v134, v229, v134, vcc
	v_cmp_lt_i32_e32 vcc, v135, v136
	global_load_dwordx4 v[212:215], v[132:133], off
	v_lshlrev_b64 v[132:133], 6, v[158:159]
	s_addc_u32 s1, s79, s1
	v_cndmask_b32_e32 v135, v229, v135, vcc
	v_lshl_add_u64 v[132:133], v[154:155], 0, v[132:133]
	v_lshl_add_u64 v[136:137], v[156:157], 2, s[0:1]
	v_lshlrev_b32_e32 v161, 2, v134
	v_lshlrev_b32_e32 v163, 2, v135
	global_load_dwordx4 v[216:219], v[132:133], off
	global_load_dwordx4 v[140:143], v[136:137], off offset:16
	global_load_dwordx4 v[144:147], v[136:137], off
	s_nop 0
	global_load_dwordx4 v[132:135], v[136:137], off offset:528
	s_nop 0
	global_load_dwordx4 v[136:139], v[136:137], off offset:512
	s_barrier
	s_branch .Lmy_g1_afterload

.Lmy_g1_afterload:
	s_and_b64 vcc, exec, s[36:37]
	s_waitcnt vmcnt(0)
	v_mov_b32_e32 v200, v181
	v_mov_b32_e32 v201, v182
	v_mov_b32_e32 v181, v183
	v_pk_add_f32 v[180:181], v[200:201], v[180:181]
	v_mov_b32_e32 v182, v185
	v_mov_b32_e32 v183, v186
	v_mov_b32_e32 v185, v187
	v_add_f32_e32 v159, v180, v181
	v_pk_add_f32 v[180:181], v[182:183], v[184:185]
	v_mov_b32_e32 v186, v189
	v_mov_b32_e32 v187, v190
	v_mov_b32_e32 v189, v191
	ds_bpermute_b32 v165, v161, v159
	v_add_f32_e32 v167, v180, v181
	v_pk_add_f32 v[182:183], v[186:187], v[188:189]
	ds_bpermute_b32 v173, v161, v167
	v_add_f32_e32 v169, v182, v183
	ds_bpermute_b32 v174, v161, v169
	s_waitcnt lgkmcnt(2)
	v_add_f32_e32 v159, v159, v165
	v_mov_b32_e32 v190, v193
	v_mov_b32_e32 v191, v194
	v_mov_b32_e32 v193, v195
	ds_bpermute_b32 v165, v163, v159
	s_waitcnt lgkmcnt(2)
	v_add_f32_e32 v167, v167, v173
	v_pk_add_f32 v[184:185], v[190:191], v[192:193]
	ds_bpermute_b32 v173, v163, v167
	v_add_f32_e32 v170, v184, v185
	s_waitcnt lgkmcnt(2)
	v_add_f32_e32 v169, v169, v174
	ds_bpermute_b32 v177, v161, v170
	ds_bpermute_b32 v174, v163, v169
	s_waitcnt lgkmcnt(3)
	v_add_f32_e32 v159, v159, v165
	v_fmamk_f32 v159, v159, 0x3a800000, v1
	s_waitcnt lgkmcnt(2)
	v_add_f32_e32 v165, v167, v173
	v_mov_b32_e32 v184, v205
	v_mov_b32_e32 v185, v206
	v_mov_b32_e32 v205, v207
	v_rsq_f32_e32 v180, v159
	v_fmamk_f32 v159, v165, 0x3a800000, v1
	v_pk_add_f32 v[184:185], v[184:185], v[204:205]
	v_rsq_f32_e32 v182, v159
	s_waitcnt lgkmcnt(0)
	v_add_f32_e32 v159, v169, v174
	v_add_f32_e32 v165, v170, v177
	v_add_f32_e32 v169, v184, v185
	ds_bpermute_b32 v167, v163, v165
	ds_bpermute_b32 v170, v161, v169
	v_fmamk_f32 v159, v159, 0x3a800000, v1
	v_rsq_f32_e32 v184, v159
	v_mov_b32_e32 v186, v209
	s_waitcnt lgkmcnt(1)
	v_add_f32_e32 v159, v165, v167
	s_waitcnt lgkmcnt(0)
	v_add_f32_e32 v165, v169, v170
	v_mov_b32_e32 v187, v210
	v_mov_b32_e32 v209, v211
	ds_bpermute_b32 v167, v163, v165
	v_pk_add_f32 v[186:187], v[186:187], v[208:209]
	v_mad_i64_i32 v[176:177], s[0:1], v176, s29, v[156:157]
	v_add_f32_e32 v169, v186, v187
	v_pk_fma_f32 v[130:131], v[130:131], v[180:181], v[146:147] op_sel_hi:[1,0,1]
	v_pk_fma_f32 v[128:129], v[128:129], v[180:181], v[144:145] op_sel_hi:[1,0,1]
	v_pk_fma_f32 v[192:193], v[126:127], v[180:181], v[142:143] op_sel_hi:[1,0,1]
	v_pk_fma_f32 v[126:127], v[124:125], v[180:181], v[140:141] op_sel_hi:[1,0,1]
	ds_bpermute_b32 v170, v161, v169
	v_cvt_pk_bf16_f32 v124, v128, v129
	v_cvt_pk_bf16_f32 v125, v130, v131
	v_cvt_pk_bf16_f32 v126, v126, v127
	v_cvt_pk_bf16_f32 v127, v192, v193
	v_lshl_add_u64 v[128:129], v[176:177], 1, s[24:25]
	global_store_dwordx4 v[128:129], v[124:127], off
	v_pk_fma_f32 v[118:119], v[118:119], v[180:181], v[138:139] op_sel_hi:[1,0,1]
	v_pk_fma_f32 v[116:117], v[116:117], v[180:181], v[136:137] op_sel_hi:[1,0,1]
	v_pk_fma_f32 v[124:125], v[110:111], v[180:181], v[134:135] op_sel_hi:[1,0,1]
	v_pk_fma_f32 v[110:111], v[108:109], v[180:181], v[132:133] op_sel_hi:[1,0,1]
	v_fmamk_f32 v159, v159, 0x3a800000, v1
	v_cvt_pk_bf16_f32 v108, v116, v117
	v_cvt_pk_bf16_f32 v109, v118, v119
	v_cvt_pk_bf16_f32 v110, v110, v111
	v_cvt_pk_bf16_f32 v111, v124, v125
	v_rsq_f32_e32 v186, v159
	s_waitcnt lgkmcnt(1)
	v_add_f32_e32 v159, v165, v167
	v_mov_b32_e32 v190, v213
	v_mov_b32_e32 v191, v214
	v_mov_b32_e32 v213, v215
	global_store_dwordx4 v[128:129], v[108:111], off offset:256
	v_mad_i64_i32 v[116:117], s[0:1], v172, s29, v[156:157]
	s_nop 0
	v_pk_fma_f32 v[110:111], v[122:123], v[182:183], v[146:147] op_sel_hi:[1,0,1]
	v_pk_fma_f32 v[108:109], v[120:121], v[182:183], v[144:145] op_sel_hi:[1,0,1]
	v_pk_fma_f32 v[114:115], v[114:115], v[182:183], v[142:143] op_sel_hi:[1,0,1]
	v_pk_fma_f32 v[112:113], v[112:113], v[182:183], v[140:141] op_sel_hi:[1,0,1]
	v_fmamk_f32 v159, v159, 0x3a800000, v1
	v_pk_add_f32 v[190:191], v[190:191], v[212:213]
	v_cvt_pk_bf16_f32 v108, v108, v109
	v_cvt_pk_bf16_f32 v109, v110, v111
	v_cvt_pk_bf16_f32 v110, v112, v113
	v_cvt_pk_bf16_f32 v111, v114, v115
	v_lshl_add_u64 v[112:113], v[116:117], 1, s[24:25]
	v_rsq_f32_e32 v188, v159
	s_waitcnt lgkmcnt(0)
	v_add_f32_e32 v159, v169, v170
	v_add_f32_e32 v167, v190, v191
	global_store_dwordx4 v[112:113], v[108:111], off
	v_pk_fma_f32 v[102:103], v[102:103], v[182:183], v[138:139] op_sel_hi:[1,0,1]
	v_pk_fma_f32 v[100:101], v[100:101], v[182:183], v[136:137] op_sel_hi:[1,0,1]
	v_pk_fma_f32 v[108:109], v[92:93], v[182:183], v[134:135] op_sel_hi:[1,0,1]
	v_pk_fma_f32 v[92:93], v[90:91], v[182:183], v[132:133] op_sel_hi:[1,0,1]
	ds_bpermute_b32 v165, v163, v159
	ds_bpermute_b32 v169, v161, v167
	v_cvt_pk_bf16_f32 v90, v100, v101
	v_cvt_pk_bf16_f32 v91, v102, v103
	v_cvt_pk_bf16_f32 v92, v92, v93
	v_cvt_pk_bf16_f32 v93, v108, v109
	v_mov_b32_e32 v190, v217
	v_mov_b32_e32 v191, v218
	v_mov_b32_e32 v217, v219
	global_store_dwordx4 v[112:113], v[90:93], off offset:256
	v_mad_i64_i32 v[100:101], s[0:1], v168, s29, v[156:157]
	s_nop 0
	v_pk_fma_f32 v[92:93], v[106:107], v[184:185], v[146:147] op_sel_hi:[1,0,1]
	v_pk_fma_f32 v[90:91], v[104:105], v[184:185], v[144:145] op_sel_hi:[1,0,1]
	v_pk_fma_f32 v[96:97], v[96:97], v[184:185], v[142:143] op_sel_hi:[1,0,1]
	v_pk_fma_f32 v[94:95], v[94:95], v[184:185], v[140:141] op_sel_hi:[1,0,1]
	v_pk_add_f32 v[190:191], v[190:191], v[216:217]
	v_cvt_pk_bf16_f32 v90, v90, v91
	v_cvt_pk_bf16_f32 v91, v92, v93
	v_cvt_pk_bf16_f32 v92, v94, v95
	v_cvt_pk_bf16_f32 v93, v96, v97
	v_lshl_add_u64 v[94:95], v[100:101], 1, s[24:25]
	v_add_f32_e32 v170, v190, v191
	global_store_dwordx4 v[94:95], v[90:93], off
	v_pk_fma_f32 v[84:85], v[84:85], v[184:185], v[138:139] op_sel_hi:[1,0,1]
	v_pk_fma_f32 v[82:83], v[82:83], v[184:185], v[136:137] op_sel_hi:[1,0,1]
	v_pk_fma_f32 v[90:91], v[76:77], v[184:185], v[134:135] op_sel_hi:[1,0,1]
	v_pk_fma_f32 v[76:77], v[74:75], v[184:185], v[132:133] op_sel_hi:[1,0,1]
	ds_bpermute_b32 v161, v161, v170
	v_cvt_pk_bf16_f32 v74, v82, v83
	v_cvt_pk_bf16_f32 v75, v84, v85
	v_cvt_pk_bf16_f32 v76, v76, v77
	v_cvt_pk_bf16_f32 v77, v90, v91
	s_waitcnt lgkmcnt(2)
	v_add_f32_e32 v159, v159, v165
	s_waitcnt lgkmcnt(1)
	v_add_f32_e32 v165, v167, v169
	global_store_dwordx4 v[94:95], v[74:77], off offset:256
	v_mad_i64_i32 v[82:83], s[0:1], v166, s29, v[156:157]
	s_nop 0
	v_pk_fma_f32 v[76:77], v[88:89], v[186:187], v[146:147] op_sel_hi:[1,0,1]
	v_pk_fma_f32 v[74:75], v[86:87], v[186:187], v[144:145] op_sel_hi:[1,0,1]
	v_pk_fma_f32 v[80:81], v[80:81], v[186:187], v[142:143] op_sel_hi:[1,0,1]
	v_pk_fma_f32 v[78:79], v[78:79], v[186:187], v[140:141] op_sel_hi:[1,0,1]
	ds_bpermute_b32 v167, v163, v165
	v_cvt_pk_bf16_f32 v74, v74, v75
	v_cvt_pk_bf16_f32 v75, v76, v77
	v_cvt_pk_bf16_f32 v76, v78, v79
	v_cvt_pk_bf16_f32 v77, v80, v81
	v_lshl_add_u64 v[78:79], v[82:83], 1, s[24:25]
	global_store_dwordx4 v[78:79], v[74:77], off
	v_pk_fma_f32 v[72:73], v[72:73], v[186:187], v[138:139] op_sel_hi:[1,0,1]
	v_pk_fma_f32 v[70:71], v[70:71], v[186:187], v[136:137] op_sel_hi:[1,0,1]
	v_pk_fma_f32 v[74:75], v[68:69], v[186:187], v[134:135] op_sel_hi:[1,0,1]
	v_pk_fma_f32 v[68:69], v[66:67], v[186:187], v[132:133] op_sel_hi:[1,0,1]
	v_fmamk_f32 v159, v159, 0x3a800000, v1
	v_cvt_pk_bf16_f32 v66, v70, v71
	v_cvt_pk_bf16_f32 v67, v72, v73
	v_cvt_pk_bf16_f32 v68, v68, v69
	v_cvt_pk_bf16_f32 v69, v74, v75
	s_waitcnt lgkmcnt(1)
	v_add_f32_e32 v161, v170, v161
	v_rsq_f32_e32 v190, v159
	global_store_dwordx4 v[78:79], v[66:69], off offset:256
	v_pk_fma_f32 v[64:65], v[64:65], v[188:189], v[146:147] op_sel_hi:[1,0,1]
	v_pk_fma_f32 v[62:63], v[62:63], v[188:189], v[144:145] op_sel_hi:[1,0,1]
	v_mad_i64_i32 v[66:67], s[0:1], v162, s29, v[156:157]
	v_pk_fma_f32 v[68:69], v[60:61], v[188:189], v[142:143] op_sel_hi:[1,0,1]
	v_pk_fma_f32 v[60:61], v[58:59], v[188:189], v[140:141] op_sel_hi:[1,0,1]
	ds_bpermute_b32 v163, v163, v161
	v_cvt_pk_bf16_f32 v58, v62, v63
	v_cvt_pk_bf16_f32 v59, v64, v65
	v_cvt_pk_bf16_f32 v60, v60, v61
	v_cvt_pk_bf16_f32 v61, v68, v69
	v_lshl_add_u64 v[62:63], v[66:67], 1, s[24:25]
	s_waitcnt lgkmcnt(1)
	v_add_f32_e32 v159, v165, v167
	global_store_dwordx4 v[62:63], v[58:61], off
	v_pk_fma_f32 v[52:53], v[52:53], v[188:189], v[138:139] op_sel_hi:[1,0,1]
	v_pk_fma_f32 v[50:51], v[50:51], v[188:189], v[136:137] op_sel_hi:[1,0,1]
	v_pk_fma_f32 v[58:59], v[44:45], v[188:189], v[134:135] op_sel_hi:[1,0,1]
	v_pk_fma_f32 v[44:45], v[42:43], v[188:189], v[132:133] op_sel_hi:[1,0,1]
	v_fmamk_f32 v159, v159, 0x3a800000, v1
	v_cvt_pk_bf16_f32 v42, v50, v51
	v_cvt_pk_bf16_f32 v43, v52, v53
	v_cvt_pk_bf16_f32 v44, v44, v45
	v_cvt_pk_bf16_f32 v45, v58, v59
	v_rsq_f32_e32 v174, v159
	global_store_dwordx4 v[62:63], v[42:45], off offset:256
	v_mad_i64_i32 v[50:51], s[0:1], v164, s29, v[156:157]
	s_nop 0
	v_pk_fma_f32 v[44:45], v[56:57], v[190:191], v[146:147] op_sel_hi:[1,0,1]
	v_pk_fma_f32 v[42:43], v[54:55], v[190:191], v[144:145] op_sel_hi:[1,0,1]
	v_pk_fma_f32 v[48:49], v[48:49], v[190:191], v[142:143] op_sel_hi:[1,0,1]
	v_pk_fma_f32 v[46:47], v[46:47], v[190:191], v[140:141] op_sel_hi:[1,0,1]
	v_cvt_pk_bf16_f32 v42, v42, v43
	v_cvt_pk_bf16_f32 v43, v44, v45
	v_cvt_pk_bf16_f32 v44, v46, v47
	v_cvt_pk_bf16_f32 v45, v48, v49
	v_lshl_add_u64 v[46:47], v[50:51], 1, s[24:25]
	s_waitcnt lgkmcnt(0)
	v_add_f32_e32 v159, v161, v163
	global_store_dwordx4 v[46:47], v[42:45], off
	v_pk_fma_f32 v[36:37], v[36:37], v[190:191], v[138:139] op_sel_hi:[1,0,1]
	v_pk_fma_f32 v[34:35], v[34:35], v[190:191], v[136:137] op_sel_hi:[1,0,1]
	v_pk_fma_f32 v[42:43], v[28:29], v[190:191], v[134:135] op_sel_hi:[1,0,1]
	v_pk_fma_f32 v[28:29], v[26:27], v[190:191], v[132:133] op_sel_hi:[1,0,1]
	v_fmamk_f32 v159, v159, 0x3a800000, v1
	v_cvt_pk_bf16_f32 v26, v34, v35
	v_cvt_pk_bf16_f32 v27, v36, v37
	v_cvt_pk_bf16_f32 v28, v28, v29
	v_cvt_pk_bf16_f32 v29, v42, v43
	v_rsq_f32_e32 v170, v159
	global_store_dwordx4 v[46:47], v[26:29], off offset:256
	v_mad_i64_i32 v[34:35], s[0:1], v160, s29, v[156:157]
	s_nop 0
	v_pk_fma_f32 v[28:29], v[40:41], v[174:175], v[146:147] op_sel_hi:[1,0,1]
	v_pk_fma_f32 v[26:27], v[38:39], v[174:175], v[144:145] op_sel_hi:[1,0,1]
	v_pk_fma_f32 v[32:33], v[32:33], v[174:175], v[142:143] op_sel_hi:[1,0,1]
	v_pk_fma_f32 v[30:31], v[30:31], v[174:175], v[140:141] op_sel_hi:[1,0,1]
	v_cvt_pk_bf16_f32 v26, v26, v27
	v_cvt_pk_bf16_f32 v27, v28, v29
	v_cvt_pk_bf16_f32 v28, v30, v31
	v_cvt_pk_bf16_f32 v29, v32, v33
	v_lshl_add_u64 v[30:31], v[34:35], 1, s[24:25]
	global_store_dwordx4 v[30:31], v[26:29], off
	v_pk_fma_f32 v[20:21], v[20:21], v[174:175], v[138:139] op_sel_hi:[1,0,1]
	v_pk_fma_f32 v[18:19], v[18:19], v[174:175], v[136:137] op_sel_hi:[1,0,1]
	v_pk_fma_f32 v[26:27], v[12:13], v[174:175], v[134:135] op_sel_hi:[1,0,1]
	v_pk_fma_f32 v[12:13], v[10:11], v[174:175], v[132:133] op_sel_hi:[1,0,1]
	v_cvt_pk_bf16_f32 v10, v18, v19
	v_cvt_pk_bf16_f32 v11, v20, v21
	v_cvt_pk_bf16_f32 v12, v12, v13
	v_cvt_pk_bf16_f32 v13, v26, v27
	global_store_dwordx4 v[30:31], v[10:13], off offset:256
	v_mad_i64_i32 v[18:19], s[0:1], v158, s29, v[156:157]
	s_nop 0
	v_pk_fma_f32 v[12:13], v[24:25], v[170:171], v[146:147] op_sel_hi:[1,0,1]
	v_pk_fma_f32 v[10:11], v[22:23], v[170:171], v[144:145] op_sel_hi:[1,0,1]
	v_pk_fma_f32 v[16:17], v[16:17], v[170:171], v[142:143] op_sel_hi:[1,0,1]
	v_pk_fma_f32 v[14:15], v[14:15], v[170:171], v[140:141] op_sel_hi:[1,0,1]
	v_cvt_pk_bf16_f32 v10, v10, v11
	v_cvt_pk_bf16_f32 v11, v12, v13
	v_cvt_pk_bf16_f32 v12, v14, v15
	v_cvt_pk_bf16_f32 v13, v16, v17
	v_lshl_add_u64 v[14:15], v[18:19], 1, s[24:25]
	global_store_dwordx4 v[14:15], v[10:13], off
	v_pk_fma_f32 v[8:9], v[8:9], v[170:171], v[138:139] op_sel_hi:[1,0,1]
	v_pk_fma_f32 v[6:7], v[6:7], v[170:171], v[136:137] op_sel_hi:[1,0,1]
	v_pk_fma_f32 v[10:11], v[4:5], v[170:171], v[134:135] op_sel_hi:[1,0,1]
	v_pk_fma_f32 v[4:5], v[2:3], v[170:171], v[132:133] op_sel_hi:[1,0,1]
	v_cvt_pk_bf16_f32 v2, v6, v7
	v_cvt_pk_bf16_f32 v3, v8, v9
	v_cvt_pk_bf16_f32 v4, v4, v5
	v_cvt_pk_bf16_f32 v5, v10, v11
	s_mov_b64 s[0:1], -1
	global_store_dwordx4 v[14:15], v[2:5], off offset:256
	s_cbranch_vccnz .LBB0_316
	s_andn2_b64 vcc, exec, s[20:21]
	s_cbranch_vccnz .LBB0_315
	s_barrier
	s_branch .LBB0_315

.Lmy_sk8:
	s_waitcnt lgkmcnt(0)
	s_setprio 1
	s_barrier
	v_mfma_f32_16x16x32_bf16 v[62:65], v[132:135], v[204:207], v[62:65]
	v_mfma_f32_16x16x32_bf16 v[58:61], v[140:143], v[204:207], v[58:61]
	v_mfma_f32_16x16x32_bf16 v[46:49], v[132:135], v[212:215], v[46:49]
	v_mfma_f32_16x16x32_bf16 v[42:45], v[140:143], v[212:215], v[42:45]
	v_mfma_f32_16x16x32_bf16 v[30:33], v[132:135], v[220:223], v[30:33]
	v_mfma_f32_16x16x32_bf16 v[26:29], v[140:143], v[220:223], v[26:29]
	v_mfma_f32_16x16x32_bf16 v[14:17], v[132:135], v[238:241], v[14:17]
	v_mfma_f32_16x16x32_bf16 v[10:13], v[140:143], v[238:241], v[10:13]
	v_mfma_f32_16x16x32_bf16 v[62:65], v[136:139], v[208:211], v[62:65]
	v_mfma_f32_16x16x32_bf16 v[58:61], v[144:147], v[208:211], v[58:61]
	v_mfma_f32_16x16x32_bf16 v[46:49], v[136:139], v[216:219], v[46:49]
	v_mfma_f32_16x16x32_bf16 v[42:45], v[144:147], v[216:219], v[42:45]
	v_mfma_f32_16x16x32_bf16 v[30:33], v[136:139], v[224:227], v[30:33]
	v_mfma_f32_16x16x32_bf16 v[26:29], v[144:147], v[224:227], v[26:29]
	v_mfma_f32_16x16x32_bf16 v[14:17], v[136:139], v[242:245], v[14:17]
	v_mfma_f32_16x16x32_bf16 v[10:13], v[144:147], v[242:245], v[10:13]
	s_setprio 0
	s_setprio 1
	v_mfma_f32_16x16x32_bf16 v[54:57], v[156:159], v[204:207], v[54:57]
	v_mfma_f32_16x16x32_bf16 v[50:53], v[192:195], v[204:207], v[50:53]
	v_mfma_f32_16x16x32_bf16 v[38:41], v[156:159], v[212:215], v[38:41]
	v_mfma_f32_16x16x32_bf16 v[34:37], v[192:195], v[212:215], v[34:37]
	v_mfma_f32_16x16x32_bf16 v[22:25], v[156:159], v[220:223], v[22:25]
	v_mfma_f32_16x16x32_bf16 v[18:21], v[192:195], v[220:223], v[18:21]
	v_mfma_f32_16x16x32_bf16 v[6:9], v[156:159], v[238:241], v[6:9]
	v_mfma_f32_16x16x32_bf16 v[2:5], v[192:195], v[238:241], v[2:5]
	v_mfma_f32_16x16x32_bf16 v[54:57], v[162:165], v[208:211], v[54:57]
	v_mfma_f32_16x16x32_bf16 v[50:53], v[200:203], v[208:211], v[50:53]
	v_mfma_f32_16x16x32_bf16 v[38:41], v[162:165], v[216:219], v[38:41]
	v_mfma_f32_16x16x32_bf16 v[34:37], v[200:203], v[216:219], v[34:37]
	v_mfma_f32_16x16x32_bf16 v[22:25], v[162:165], v[224:227], v[22:25]
	v_mfma_f32_16x16x32_bf16 v[18:21], v[200:203], v[224:227], v[18:21]
	v_mfma_f32_16x16x32_bf16 v[6:9], v[162:165], v[242:245], v[6:9]
	v_mfma_f32_16x16x32_bf16 v[2:5], v[200:203], v[242:245], v[2:5]
	s_setprio 0
	s_barrier
	s_add_i32 s6, 0, 0x18000
	s_add_i32 s7, 0, 0x1c000
	v_add_u32_e32 v144, s6, v189
	v_add_u32_e32 v160, s7, v189
	ds_read_b128 v[132:135], v144
	ds_read_b128 v[136:139], v144 offset:1024
	ds_read_b128 v[140:143], v144 offset:2048
	ds_read_b128 v[144:147], v144 offset:3072
	ds_read_b128 v[156:159], v160
	ds_read_b128 v[162:165], v160 offset:1024
	ds_read_b128 v[192:195], v160 offset:2048
	ds_read_b128 v[200:203], v160 offset:3072
	s_add_u32 s4, s68, 0x40000
	s_addc_u32 s5, s69, 0
	v_lshl_add_u64 v[246:247], s[4:5], 0, v[98:99]
	s_add_i32 m0, s44, 0x4000
	ds_read_b128 v[204:207], v191 offset:32768
	ds_read_b128 v[208:211], v191 offset:33792
	ds_read_b128 v[212:215], v191 offset:34816
	ds_read_b128 v[216:219], v191 offset:35840
	ds_read_b128 v[220:223], v191 offset:36864
	ds_read_b128 v[224:227], v191 offset:37888
	ds_read_b128 v[238:241], v191 offset:38912
	ds_read_b128 v[242:245], v191 offset:39936
	global_load_lds_dwordx4 v[246:247], off
	v_lshl_add_u64 v[246:247], s[4:5], 0, v[150:151]
	s_add_i32 m0, s44, 0x6000
	s_nop 0
	global_load_lds_dwordx4 v[246:247], off
	s_waitcnt vmcnt(8)
	s_waitcnt lgkmcnt(0)
	s_setprio 1
	s_barrier
	v_mfma_f32_16x16x32_bf16 v[128:131], v[132:135], v[204:207], v[128:131]
	v_mfma_f32_16x16x32_bf16 v[124:127], v[140:143], v[204:207], v[124:127]
	v_mfma_f32_16x16x32_bf16 v[112:115], v[132:135], v[212:215], v[112:115]
	v_mfma_f32_16x16x32_bf16 v[108:111], v[140:143], v[212:215], v[108:111]
	v_mfma_f32_16x16x32_bf16 v[94:97], v[132:135], v[220:223], v[94:97]
	v_mfma_f32_16x16x32_bf16 v[90:93], v[140:143], v[220:223], v[90:93]
	v_mfma_f32_16x16x32_bf16 v[78:81], v[132:135], v[238:241], v[78:81]
	v_mfma_f32_16x16x32_bf16 v[74:77], v[140:143], v[238:241], v[74:77]
	v_mfma_f32_16x16x32_bf16 v[128:131], v[136:139], v[208:211], v[128:131]
	v_mfma_f32_16x16x32_bf16 v[124:127], v[144:147], v[208:211], v[124:127]
	v_mfma_f32_16x16x32_bf16 v[112:115], v[136:139], v[216:219], v[112:115]
	v_mfma_f32_16x16x32_bf16 v[108:111], v[144:147], v[216:219], v[108:111]
	v_mfma_f32_16x16x32_bf16 v[94:97], v[136:139], v[224:227], v[94:97]
	v_mfma_f32_16x16x32_bf16 v[90:93], v[144:147], v[224:227], v[90:93]
	v_mfma_f32_16x16x32_bf16 v[78:81], v[136:139], v[242:245], v[78:81]
	v_mfma_f32_16x16x32_bf16 v[74:77], v[144:147], v[242:245], v[74:77]
	s_setprio 0
	s_setprio 1
	v_mfma_f32_16x16x32_bf16 v[120:123], v[156:159], v[204:207], v[120:123]
	v_mfma_f32_16x16x32_bf16 v[116:119], v[192:195], v[204:207], v[116:119]
	v_mfma_f32_16x16x32_bf16 v[104:107], v[156:159], v[212:215], v[104:107]
	v_mfma_f32_16x16x32_bf16 v[100:103], v[192:195], v[212:215], v[100:103]
	v_mfma_f32_16x16x32_bf16 v[86:89], v[156:159], v[220:223], v[86:89]
	v_mfma_f32_16x16x32_bf16 v[82:85], v[192:195], v[220:223], v[82:85]
	v_mfma_f32_16x16x32_bf16 v[70:73], v[156:159], v[238:241], v[70:73]
	v_mfma_f32_16x16x32_bf16 v[66:69], v[192:195], v[238:241], v[66:69]
	v_mfma_f32_16x16x32_bf16 v[120:123], v[162:165], v[208:211], v[120:123]
	v_mfma_f32_16x16x32_bf16 v[116:119], v[200:203], v[208:211], v[116:119]
	v_mfma_f32_16x16x32_bf16 v[104:107], v[162:165], v[216:219], v[104:107]
	v_mfma_f32_16x16x32_bf16 v[100:103], v[200:203], v[216:219], v[100:103]
	v_mfma_f32_16x16x32_bf16 v[86:89], v[162:165], v[224:227], v[86:89]
	v_mfma_f32_16x16x32_bf16 v[82:85], v[200:203], v[224:227], v[82:85]
	v_mfma_f32_16x16x32_bf16 v[70:73], v[162:165], v[242:245], v[70:73]
	v_mfma_f32_16x16x32_bf16 v[66:69], v[200:203], v[242:245], v[66:69]
	s_setprio 0
	s_barrier
	s_add_i32 s4, s6, s70
	v_lshl_add_u64 v[166:167], v[166:167], 0, s[42:43]
	s_mov_b32 m0, s4
	ds_read_b128 v[204:207], v191 offset:49152
	ds_read_b128 v[208:211], v191 offset:50176
	ds_read_b128 v[212:215], v191 offset:51200
	ds_read_b128 v[216:219], v191 offset:52224
	ds_read_b128 v[220:223], v191 offset:53248
	ds_read_b128 v[224:227], v191 offset:54272
	ds_read_b128 v[238:241], v191 offset:55296
	ds_read_b128 v[242:245], v191 offset:56320
	global_load_lds_dwordx4 v[166:167], off
	s_add_i32 m0, s4, 0x2000
	s_add_u32 s4, s56, 0x40080
	v_lshl_add_u64 v[166:167], v[170:171], 0, s[42:43]
	s_addc_u32 s5, s57, 0
	s_add_i32 s6, s7, s70
	global_load_lds_dwordx4 v[166:167], off
	v_lshl_add_u64 v[166:167], s[4:5], 0, v[148:149]
	s_mov_b32 m0, s6
	s_nop 0
	global_load_lds_dwordx4 v[166:167], off
	v_lshl_add_u64 v[166:167], s[4:5], 0, v[152:153]
	s_add_i32 m0, s6, 0x2000
	s_nop 0
	global_load_lds_dwordx4 v[166:167], off
	v_lshl_add_u64 v[166:167], v[176:177], 0, s[42:43]
	s_add_i32 m0, s44, 0x8000
	s_nop 0
	global_load_lds_dwordx4 v[166:167], off
	v_lshl_add_u64 v[166:167], v[180:181], 0, s[42:43]
	s_add_i32 m0, s44, 0xa000
	s_nop 0
	global_load_lds_dwordx4 v[166:167], off
	s_waitcnt vmcnt(8)
	s_waitcnt lgkmcnt(0)
	s_setprio 1
	s_barrier
	v_mfma_f32_16x16x32_bf16 v[62:65], v[132:135], v[204:207], v[62:65]
	v_mfma_f32_16x16x32_bf16 v[58:61], v[140:143], v[204:207], v[58:61]
	v_mfma_f32_16x16x32_bf16 v[46:49], v[132:135], v[212:215], v[46:49]
	v_mfma_f32_16x16x32_bf16 v[42:45], v[140:143], v[212:215], v[42:45]
	v_mfma_f32_16x16x32_bf16 v[30:33], v[132:135], v[220:223], v[30:33]
	v_mfma_f32_16x16x32_bf16 v[26:29], v[140:143], v[220:223], v[26:29]
	v_mfma_f32_16x16x32_bf16 v[14:17], v[132:135], v[238:241], v[14:17]
	v_mfma_f32_16x16x32_bf16 v[10:13], v[140:143], v[238:241], v[10:13]
	v_mfma_f32_16x16x32_bf16 v[62:65], v[136:139], v[208:211], v[62:65]
	v_mfma_f32_16x16x32_bf16 v[58:61], v[144:147], v[208:211], v[58:61]
	v_mfma_f32_16x16x32_bf16 v[46:49], v[136:139], v[216:219], v[46:49]
	v_mfma_f32_16x16x32_bf16 v[42:45], v[144:147], v[216:219], v[42:45]
	v_mfma_f32_16x16x32_bf16 v[30:33], v[136:139], v[224:227], v[30:33]
	v_mfma_f32_16x16x32_bf16 v[26:29], v[144:147], v[224:227], v[26:29]
	v_mfma_f32_16x16x32_bf16 v[14:17], v[136:139], v[242:245], v[14:17]
	v_mfma_f32_16x16x32_bf16 v[10:13], v[144:147], v[242:245], v[10:13]
	s_setprio 0
	s_setprio 1
	v_mfma_f32_16x16x32_bf16 v[54:57], v[156:159], v[204:207], v[54:57]
	v_mfma_f32_16x16x32_bf16 v[50:53], v[192:195], v[204:207], v[50:53]
	v_mfma_f32_16x16x32_bf16 v[38:41], v[156:159], v[212:215], v[38:41]
	v_mfma_f32_16x16x32_bf16 v[34:37], v[192:195], v[212:215], v[34:37]
	v_mfma_f32_16x16x32_bf16 v[22:25], v[156:159], v[220:223], v[22:25]
	v_mfma_f32_16x16x32_bf16 v[18:21], v[192:195], v[220:223], v[18:21]
	v_mfma_f32_16x16x32_bf16 v[6:9], v[156:159], v[238:241], v[6:9]
	v_mfma_f32_16x16x32_bf16 v[2:5], v[192:195], v[238:241], v[2:5]
	v_mfma_f32_16x16x32_bf16 v[54:57], v[162:165], v[208:211], v[54:57]
	v_mfma_f32_16x16x32_bf16 v[50:53], v[200:203], v[208:211], v[50:53]
	v_mfma_f32_16x16x32_bf16 v[38:41], v[162:165], v[216:219], v[38:41]
	v_mfma_f32_16x16x32_bf16 v[34:37], v[200:203], v[216:219], v[34:37]
	v_mfma_f32_16x16x32_bf16 v[22:25], v[162:165], v[224:227], v[22:25]
	v_mfma_f32_16x16x32_bf16 v[18:21], v[200:203], v[224:227], v[18:21]
	v_mfma_f32_16x16x32_bf16 v[6:9], v[162:165], v[242:245], v[6:9]
	v_mfma_f32_16x16x32_bf16 v[2:5], v[200:203], v[242:245], v[2:5]
	s_setprio 0
	s_barrier
	s_mov_b32 s100, 0
	s_add_i32 s92, s92, 2
	s_add_u32 s40, s40, 0x100
	s_addc_u32 s41, s41, 0
	s_add_u32 s90, s90, 0x100
	s_addc_u32 s91, s91, 0
	s_cmp_gt_u32 s92, 13
	s_cbranch_scc0 .LBB0_1011
	s_mov_b32 s100, 1
	s_and_b64 vcc, exec, s[0:1]
	s_cbranch_vccz .LBB0_1014
	s_lshl_b32 s4, s77, 8
	v_add_u32_e32 v162, s4, v188
	v_ashrrev_i32_e32 v163, 31, v162
	v_or_b32_e32 v180, 16, v162
	v_lshlrev_b64 v[132:133], 6, v[162:163]
	v_ashrrev_i32_e32 v181, 31, v180
	v_or_b32_e32 v176, 32, v162
	v_lshl_add_u64 v[132:133], v[154:155], 0, v[132:133]
	v_lshlrev_b64 v[134:135], 6, v[180:181]
	v_ashrrev_i32_e32 v177, 31, v176
	v_lshl_add_u64 v[134:135], v[154:155], 0, v[134:135]
	global_load_dwordx4 v[192:195], v[132:133], off
	global_load_dwordx4 v[200:203], v[134:135], off
	v_lshlrev_b64 v[132:133], 6, v[176:177]
	v_lshl_add_u64 v[132:133], v[154:155], 0, v[132:133]
	global_load_dwordx4 v[204:207], v[132:133], off
	v_or_b32_e32 v170, 48, v162
	v_ashrrev_i32_e32 v171, 31, v170
	v_lshlrev_b64 v[132:133], 6, v[170:171]
	v_lshl_add_u64 v[132:133], v[154:155], 0, v[132:133]
	global_load_dwordx4 v[208:211], v[132:133], off
	v_add_u32_e32 v166, 0x80, v162
	v_ashrrev_i32_e32 v167, 31, v166
	v_lshlrev_b64 v[132:133], 6, v[166:167]
	v_lshl_add_u64 v[132:133], v[154:155], 0, v[132:133]
	global_load_dwordx4 v[212:215], v[132:133], off
	v_add_u32_e32 v164, 0x90, v162
	v_and_b32_e32 v132, 64, v229
	v_ashrrev_i32_e32 v165, 31, v164
	v_add_u32_e32 v136, 64, v132
	v_lshlrev_b64 v[132:133], 6, v[164:165]
	v_lshl_add_u64 v[132:133], v[154:155], 0, v[132:133]
	global_load_dwordx4 v[216:219], v[132:133], off
	v_add_u32_e32 v158, 0xa0, v162
	v_ashrrev_i32_e32 v159, 31, v158
	v_add_u32_e32 v156, 0xb0, v162
	v_lshlrev_b64 v[132:133], 6, v[158:159]
	v_ashrrev_i32_e32 v157, 31, v156
	v_lshl_add_u64 v[132:133], v[154:155], 0, v[132:133]
	global_load_dwordx4 v[220:223], v[132:133], off
	v_lshlrev_b64 v[132:133], 6, v[156:157]
	v_lshl_add_u64 v[132:133], v[154:155], 0, v[132:133]
	global_load_dwordx4 v[224:227], v[132:133], off
	s_addk_i32 s4, 0xc000
	s_lshr_b32 s4, s4, 12
	s_ashr_i32 s5, s77, 5
	s_add_i32 s4, s4, 2
	s_cmp_lt_i32 s77, 64
	s_cselect_b32 s4, s5, s4
	s_ashr_i32 s5, s4, 31
	v_xor_b32_e32 v134, 16, v229
	s_lshl_b64 s[4:5], s[4:5], 14
	v_lshl_or_b32 v238, s79, 8, v190
	v_xor_b32_e32 v135, 32, v229
	v_cmp_lt_i32_e32 vcc, v134, v136
	s_add_u32 s4, s71, s4
	v_ashrrev_i32_e32 v239, 31, v238
	v_cndmask_b32_e32 v134, v229, v134, vcc
	v_cmp_lt_i32_e32 vcc, v135, v136
	s_addc_u32 s5, s74, s5
	v_lshl_add_u64 v[136:137], v[238:239], 2, s[4:5]
	v_cndmask_b32_e32 v135, v229, v135, vcc
	v_lshlrev_b32_e32 v160, 2, v134
	v_lshlrev_b32_e32 v168, 2, v135
	global_load_dwordx4 v[140:143], v[136:137], off offset:16
	global_load_dwordx4 v[144:147], v[136:137], off
	global_load_dwordx4 v[132:135], v[136:137], off offset:528
	s_nop 0
	global_load_dwordx4 v[136:139], v[136:137], off offset:512
	s_barrier
	s_branch .Lmy_g3_afterload

.Lmy_g3_afterload:
	s_andn2_b64 vcc, exec, s[36:37]
	s_mov_b64 s[36:37], -1
	s_waitcnt vmcnt(0)
	v_mov_b32_e32 v240, v193
	v_mov_b32_e32 v241, v194
	v_mov_b32_e32 v193, v195
	v_pk_add_f32 v[192:193], v[240:241], v[192:193]
	v_mov_b32_e32 v194, v201
	v_mov_b32_e32 v195, v202
	v_mov_b32_e32 v201, v203
	v_add_f32_e32 v172, v192, v193
	v_pk_add_f32 v[192:193], v[194:195], v[200:201]
	v_mov_b32_e32 v202, v205
	v_mov_b32_e32 v203, v206
	v_mov_b32_e32 v205, v207
	ds_bpermute_b32 v174, v160, v172
	v_add_f32_e32 v178, v192, v193
	v_pk_add_f32 v[194:195], v[202:203], v[204:205]
	ds_bpermute_b32 v192, v160, v178
	v_add_f32_e32 v182, v194, v195
	ds_bpermute_b32 v194, v160, v182
	s_waitcnt lgkmcnt(2)
	v_add_f32_e32 v172, v172, v174
	ds_bpermute_b32 v174, v168, v172
	s_waitcnt lgkmcnt(2)
	v_add_f32_e32 v178, v178, v192
	v_mov_b32_e32 v206, v209
	v_mov_b32_e32 v207, v210
	v_mov_b32_e32 v209, v211
	ds_bpermute_b32 v192, v168, v178
	v_pk_add_f32 v[200:201], v[206:207], v[208:209]
	s_waitcnt lgkmcnt(2)
	v_add_f32_e32 v182, v182, v194
	v_add_f32_e32 v193, v200, v201
	ds_bpermute_b32 v200, v168, v182
	ds_bpermute_b32 v195, v160, v193
	s_waitcnt lgkmcnt(3)
	v_add_f32_e32 v172, v172, v174
	v_fmamk_f32 v172, v172, 0x3a800000, v1
	s_waitcnt lgkmcnt(2)
	v_add_f32_e32 v174, v178, v192
	v_rsq_f32_e32 v192, v172
	v_fmamk_f32 v172, v174, 0x3a800000, v1
	v_rsq_f32_e32 v194, v172
	s_waitcnt lgkmcnt(1)
	v_add_f32_e32 v172, v182, v200
	v_mov_b32_e32 v200, v213
	v_mov_b32_e32 v201, v214
	v_mov_b32_e32 v213, v215
	v_pk_add_f32 v[200:201], v[200:201], v[212:213]
	s_waitcnt lgkmcnt(0)
	v_add_f32_e32 v174, v193, v195
	v_add_f32_e32 v193, v200, v201
	ds_bpermute_b32 v178, v168, v174
	ds_bpermute_b32 v195, v160, v193
	v_fmamk_f32 v172, v172, 0x3a800000, v1
	v_rsq_f32_e32 v182, v172
	v_mov_b32_e32 v200, v217
	s_waitcnt lgkmcnt(1)
	v_add_f32_e32 v172, v174, v178
	s_waitcnt lgkmcnt(0)
	v_add_f32_e32 v174, v193, v195
	v_mov_b32_e32 v201, v218
	v_mov_b32_e32 v217, v219
	ds_bpermute_b32 v193, v168, v174
	v_pk_add_f32 v[200:201], v[200:201], v[216:217]
	v_fmamk_f32 v172, v172, 0x3a800000, v1
	v_add_f32_e32 v195, v200, v201
	ds_bpermute_b32 v200, v160, v195
	v_rsq_f32_e32 v178, v172
	s_waitcnt lgkmcnt(1)
	v_add_f32_e32 v172, v174, v193
	v_fmamk_f32 v172, v172, 0x3a800000, v1
	v_rsq_f32_e32 v174, v172
	s_waitcnt lgkmcnt(0)
	v_add_f32_e32 v172, v195, v200
	v_mov_b32_e32 v200, v221
	v_mov_b32_e32 v201, v222
	v_mov_b32_e32 v221, v223
	v_pk_add_f32 v[200:201], v[200:201], v[220:221]
	ds_bpermute_b32 v193, v168, v172
	v_add_f32_e32 v195, v200, v201
	v_mov_b32_e32 v200, v225
	v_mov_b32_e32 v201, v226
	v_mov_b32_e32 v225, v227
	v_pk_add_f32 v[200:201], v[200:201], v[224:225]
	ds_bpermute_b32 v202, v160, v195
	v_add_f32_e32 v200, v200, v201
	ds_bpermute_b32 v160, v160, v200
	s_waitcnt lgkmcnt(2)
	v_add_f32_e32 v172, v172, v193
	v_pk_fma_f32 v[94:95], v[94:95], v[182:183], v[144:145] op_sel_hi:[1,0,1]
	s_waitcnt lgkmcnt(1)
	v_add_f32_e32 v193, v195, v202
	ds_bpermute_b32 v195, v168, v193
	s_waitcnt lgkmcnt(1)
	v_add_f32_e32 v160, v200, v160
	ds_bpermute_b32 v200, v168, v160
	v_pk_fma_f32 v[128:129], v[128:129], v[192:193], v[144:145] op_sel_hi:[1,0,1]
	v_pk_fma_f32 v[130:131], v[130:131], v[192:193], v[146:147] op_sel_hi:[1,0,1]
	v_pk_fma_f32 v[126:127], v[126:127], v[192:193], v[142:143] op_sel_hi:[1,0,1]
	v_pk_fma_f32 v[124:125], v[124:125], v[192:193], v[140:141] op_sel_hi:[1,0,1]
	v_max_f32_e32 v128, 0, v128
	v_max_f32_e32 v129, 0, v129
	s_waitcnt lgkmcnt(0)
	v_add_f32_e32 v160, v160, v200
	v_lshlrev_b64 v[200:201], 13, v[162:163]
	v_max_f32_e32 v124, 0, v124
	v_max_f32_e32 v125, 0, v125
	v_max_f32_e32 v130, 0, v130
	v_max_f32_e32 v126, 0, v126
	v_max_f32_e32 v131, 0, v131
	v_max_f32_e32 v127, 0, v127
	v_pk_mul_f32 v[128:129], v[128:129], v[128:129]
	v_lshlrev_b64 v[162:163], 1, v[238:239]
	v_pk_mul_f32 v[130:131], v[130:131], v[130:131]
	v_pk_mul_f32 v[202:203], v[126:127], v[126:127]
	v_pk_mul_f32 v[126:127], v[124:125], v[124:125]
	v_cvt_pk_bf16_f32 v124, v128, v129
	v_lshl_add_u64 v[128:129], s[24:25], 0, v[200:201]
	v_pk_fma_f32 v[122:123], v[122:123], v[192:193], v[138:139] op_sel_hi:[1,0,1]
	v_pk_fma_f32 v[120:121], v[120:121], v[192:193], v[136:137] op_sel_hi:[1,0,1]
	v_pk_fma_f32 v[118:119], v[118:119], v[192:193], v[134:135] op_sel_hi:[1,0,1]
	v_pk_fma_f32 v[116:117], v[116:117], v[192:193], v[132:133] op_sel_hi:[1,0,1]
	v_cvt_pk_bf16_f32 v125, v130, v131
	v_cvt_pk_bf16_f32 v126, v126, v127
	v_cvt_pk_bf16_f32 v127, v202, v203
	v_lshl_add_u64 v[128:129], v[128:129], 0, v[162:163]
	v_max_f32_e32 v120, 0, v120
	v_max_f32_e32 v116, 0, v116
	v_max_f32_e32 v121, 0, v121
	v_max_f32_e32 v117, 0, v117
	v_max_f32_e32 v122, 0, v122
	v_max_f32_e32 v118, 0, v118
	v_max_f32_e32 v123, 0, v123
	v_max_f32_e32 v119, 0, v119
	global_store_dwordx4 v[128:129], v[124:127], off
	v_pk_mul_f32 v[122:123], v[122:123], v[122:123]
	v_pk_mul_f32 v[120:121], v[120:121], v[120:121]
	v_pk_mul_f32 v[124:125], v[118:119], v[118:119]
	v_pk_mul_f32 v[118:119], v[116:117], v[116:117]
	v_pk_fma_f32 v[112:113], v[112:113], v[194:195], v[144:145] op_sel_hi:[1,0,1]
	v_cvt_pk_bf16_f32 v116, v120, v121
	v_cvt_pk_bf16_f32 v117, v122, v123
	v_cvt_pk_bf16_f32 v118, v118, v119
	v_cvt_pk_bf16_f32 v119, v124, v125
	v_pk_fma_f32 v[114:115], v[114:115], v[194:195], v[146:147] op_sel_hi:[1,0,1]
	v_pk_fma_f32 v[110:111], v[110:111], v[194:195], v[142:143] op_sel_hi:[1,0,1]
	v_pk_fma_f32 v[108:109], v[108:109], v[194:195], v[140:141] op_sel_hi:[1,0,1]
	v_max_f32_e32 v112, 0, v112
	v_max_f32_e32 v113, 0, v113
	global_store_dwordx4 v[128:129], v[116:119], off offset:256
	v_max_f32_e32 v108, 0, v108
	v_max_f32_e32 v109, 0, v109
	v_lshlrev_b64 v[116:117], 13, v[180:181]
	v_max_f32_e32 v114, 0, v114
	v_max_f32_e32 v110, 0, v110
	v_max_f32_e32 v115, 0, v115
	v_max_f32_e32 v111, 0, v111
	v_pk_mul_f32 v[112:113], v[112:113], v[112:113]
	v_pk_mul_f32 v[114:115], v[114:115], v[114:115]
	v_pk_mul_f32 v[118:119], v[110:111], v[110:111]
	v_pk_mul_f32 v[110:111], v[108:109], v[108:109]
	v_cvt_pk_bf16_f32 v108, v112, v113
	v_lshl_add_u64 v[112:113], s[24:25], 0, v[116:117]
	v_pk_fma_f32 v[106:107], v[106:107], v[194:195], v[138:139] op_sel_hi:[1,0,1]
	v_pk_fma_f32 v[104:105], v[104:105], v[194:195], v[136:137] op_sel_hi:[1,0,1]
	v_pk_fma_f32 v[102:103], v[102:103], v[194:195], v[134:135] op_sel_hi:[1,0,1]
	v_pk_fma_f32 v[100:101], v[100:101], v[194:195], v[132:133] op_sel_hi:[1,0,1]
	v_cvt_pk_bf16_f32 v109, v114, v115
	v_cvt_pk_bf16_f32 v110, v110, v111
	v_cvt_pk_bf16_f32 v111, v118, v119
	v_lshl_add_u64 v[112:113], v[112:113], 0, v[162:163]
	v_max_f32_e32 v104, 0, v104
	v_max_f32_e32 v100, 0, v100
	v_max_f32_e32 v105, 0, v105
	v_max_f32_e32 v101, 0, v101
	v_max_f32_e32 v106, 0, v106
	v_max_f32_e32 v102, 0, v102
	v_max_f32_e32 v107, 0, v107
	v_max_f32_e32 v103, 0, v103
	global_store_dwordx4 v[112:113], v[108:111], off
	v_pk_mul_f32 v[106:107], v[106:107], v[106:107]
	v_pk_mul_f32 v[104:105], v[104:105], v[104:105]
	v_pk_mul_f32 v[108:109], v[102:103], v[102:103]
	v_pk_mul_f32 v[102:103], v[100:101], v[100:101]
	v_cvt_pk_bf16_f32 v100, v104, v105
	v_cvt_pk_bf16_f32 v101, v106, v107
	v_cvt_pk_bf16_f32 v102, v102, v103
	v_cvt_pk_bf16_f32 v103, v108, v109
	v_pk_fma_f32 v[96:97], v[96:97], v[182:183], v[146:147] op_sel_hi:[1,0,1]
	v_pk_fma_f32 v[92:93], v[92:93], v[182:183], v[142:143] op_sel_hi:[1,0,1]
	v_pk_fma_f32 v[90:91], v[90:91], v[182:183], v[140:141] op_sel_hi:[1,0,1]
	v_max_f32_e32 v94, 0, v94
	v_max_f32_e32 v95, 0, v95
	global_store_dwordx4 v[112:113], v[100:103], off offset:256
	v_max_f32_e32 v90, 0, v90
	v_max_f32_e32 v91, 0, v91
	v_lshlrev_b64 v[100:101], 13, v[176:177]
	v_max_f32_e32 v96, 0, v96
	v_max_f32_e32 v92, 0, v92
	v_max_f32_e32 v97, 0, v97
	v_max_f32_e32 v93, 0, v93
	v_pk_mul_f32 v[94:95], v[94:95], v[94:95]
	v_pk_mul_f32 v[96:97], v[96:97], v[96:97]
	v_pk_mul_f32 v[102:103], v[92:93], v[92:93]
	v_pk_mul_f32 v[92:93], v[90:91], v[90:91]
	v_cvt_pk_bf16_f32 v90, v94, v95
	v_lshl_add_u64 v[94:95], s[24:25], 0, v[100:101]
	v_pk_fma_f32 v[88:89], v[88:89], v[182:183], v[138:139] op_sel_hi:[1,0,1]
	v_pk_fma_f32 v[86:87], v[86:87], v[182:183], v[136:137] op_sel_hi:[1,0,1]
	v_pk_fma_f32 v[84:85], v[84:85], v[182:183], v[134:135] op_sel_hi:[1,0,1]
	v_pk_fma_f32 v[82:83], v[82:83], v[182:183], v[132:133] op_sel_hi:[1,0,1]
	v_cvt_pk_bf16_f32 v91, v96, v97
	v_cvt_pk_bf16_f32 v92, v92, v93
	v_cvt_pk_bf16_f32 v93, v102, v103
	v_lshl_add_u64 v[94:95], v[94:95], 0, v[162:163]
	v_max_f32_e32 v86, 0, v86
	v_max_f32_e32 v82, 0, v82
	v_max_f32_e32 v87, 0, v87
	v_max_f32_e32 v83, 0, v83
	v_max_f32_e32 v88, 0, v88
	v_max_f32_e32 v84, 0, v84
	v_max_f32_e32 v89, 0, v89
	v_max_f32_e32 v85, 0, v85
	global_store_dwordx4 v[94:95], v[90:93], off
	v_pk_mul_f32 v[88:89], v[88:89], v[88:89]
	v_pk_mul_f32 v[86:87], v[86:87], v[86:87]
	v_pk_mul_f32 v[90:91], v[84:85], v[84:85]
	v_pk_mul_f32 v[84:85], v[82:83], v[82:83]
	v_pk_fma_f32 v[78:79], v[78:79], v[178:179], v[144:145] op_sel_hi:[1,0,1]
	v_cvt_pk_bf16_f32 v82, v86, v87
	v_cvt_pk_bf16_f32 v83, v88, v89
	v_cvt_pk_bf16_f32 v84, v84, v85
	v_cvt_pk_bf16_f32 v85, v90, v91
	v_pk_fma_f32 v[80:81], v[80:81], v[178:179], v[146:147] op_sel_hi:[1,0,1]
	v_pk_fma_f32 v[76:77], v[76:77], v[178:179], v[142:143] op_sel_hi:[1,0,1]
	v_pk_fma_f32 v[74:75], v[74:75], v[178:179], v[140:141] op_sel_hi:[1,0,1]
	v_max_f32_e32 v78, 0, v78
	v_max_f32_e32 v79, 0, v79
	global_store_dwordx4 v[94:95], v[82:85], off offset:256
	v_max_f32_e32 v74, 0, v74
	v_max_f32_e32 v75, 0, v75
	v_lshlrev_b64 v[82:83], 13, v[170:171]
	v_max_f32_e32 v80, 0, v80
	v_max_f32_e32 v76, 0, v76
	v_max_f32_e32 v81, 0, v81
	v_max_f32_e32 v77, 0, v77
	v_pk_mul_f32 v[78:79], v[78:79], v[78:79]
	v_pk_mul_f32 v[80:81], v[80:81], v[80:81]
	v_pk_mul_f32 v[84:85], v[76:77], v[76:77]
	v_pk_mul_f32 v[76:77], v[74:75], v[74:75]
	v_cvt_pk_bf16_f32 v74, v78, v79
	v_lshl_add_u64 v[78:79], s[24:25], 0, v[82:83]
	v_pk_fma_f32 v[72:73], v[72:73], v[178:179], v[138:139] op_sel_hi:[1,0,1]
	v_pk_fma_f32 v[70:71], v[70:71], v[178:179], v[136:137] op_sel_hi:[1,0,1]
	v_pk_fma_f32 v[68:69], v[68:69], v[178:179], v[134:135] op_sel_hi:[1,0,1]
	v_pk_fma_f32 v[66:67], v[66:67], v[178:179], v[132:133] op_sel_hi:[1,0,1]
	v_cvt_pk_bf16_f32 v75, v80, v81
	v_cvt_pk_bf16_f32 v76, v76, v77
	v_cvt_pk_bf16_f32 v77, v84, v85
	v_lshl_add_u64 v[78:79], v[78:79], 0, v[162:163]
	v_max_f32_e32 v70, 0, v70
	v_max_f32_e32 v66, 0, v66
	v_max_f32_e32 v71, 0, v71
	v_max_f32_e32 v67, 0, v67
	v_max_f32_e32 v72, 0, v72
	v_max_f32_e32 v68, 0, v68
	v_max_f32_e32 v73, 0, v73
	v_max_f32_e32 v69, 0, v69
	v_fmamk_f32 v172, v172, 0x3a800000, v1
	global_store_dwordx4 v[78:79], v[74:77], off
	v_pk_mul_f32 v[72:73], v[72:73], v[72:73]
	v_pk_mul_f32 v[70:71], v[70:71], v[70:71]
	v_pk_mul_f32 v[74:75], v[68:69], v[68:69]
	v_pk_mul_f32 v[68:69], v[66:67], v[66:67]
	v_pk_fma_f32 v[62:63], v[62:63], v[174:175], v[144:145] op_sel_hi:[1,0,1]
	v_rsq_f32_e32 v172, v172
	v_cvt_pk_bf16_f32 v66, v70, v71
	v_cvt_pk_bf16_f32 v67, v72, v73
	v_cvt_pk_bf16_f32 v68, v68, v69
	v_cvt_pk_bf16_f32 v69, v74, v75
	v_pk_fma_f32 v[64:65], v[64:65], v[174:175], v[146:147] op_sel_hi:[1,0,1]
	v_pk_fma_f32 v[60:61], v[60:61], v[174:175], v[142:143] op_sel_hi:[1,0,1]
	v_pk_fma_f32 v[58:59], v[58:59], v[174:175], v[140:141] op_sel_hi:[1,0,1]
	v_max_f32_e32 v62, 0, v62
	v_max_f32_e32 v63, 0, v63
	global_store_dwordx4 v[78:79], v[66:69], off offset:256
	v_max_f32_e32 v58, 0, v58
	v_max_f32_e32 v59, 0, v59
	v_lshlrev_b64 v[66:67], 13, v[166:167]
	v_max_f32_e32 v64, 0, v64
	v_max_f32_e32 v60, 0, v60
	v_max_f32_e32 v65, 0, v65
	v_max_f32_e32 v61, 0, v61
	v_pk_mul_f32 v[62:63], v[62:63], v[62:63]
	v_pk_mul_f32 v[64:65], v[64:65], v[64:65]
	v_pk_mul_f32 v[68:69], v[60:61], v[60:61]
	v_pk_mul_f32 v[60:61], v[58:59], v[58:59]
	v_cvt_pk_bf16_f32 v58, v62, v63
	v_lshl_add_u64 v[62:63], s[24:25], 0, v[66:67]
	v_pk_fma_f32 v[56:57], v[56:57], v[174:175], v[138:139] op_sel_hi:[1,0,1]
	v_pk_fma_f32 v[54:55], v[54:55], v[174:175], v[136:137] op_sel_hi:[1,0,1]
	v_pk_fma_f32 v[52:53], v[52:53], v[174:175], v[134:135] op_sel_hi:[1,0,1]
	v_pk_fma_f32 v[50:51], v[50:51], v[174:175], v[132:133] op_sel_hi:[1,0,1]
	v_add_f32_e32 v168, v193, v195
	v_cvt_pk_bf16_f32 v59, v64, v65
	v_cvt_pk_bf16_f32 v60, v60, v61
	v_cvt_pk_bf16_f32 v61, v68, v69
	v_lshl_add_u64 v[62:63], v[62:63], 0, v[162:163]
	v_max_f32_e32 v54, 0, v54
	v_max_f32_e32 v50, 0, v50
	v_max_f32_e32 v55, 0, v55
	v_max_f32_e32 v51, 0, v51
	v_max_f32_e32 v56, 0, v56
	v_max_f32_e32 v52, 0, v52
	v_max_f32_e32 v57, 0, v57
	v_max_f32_e32 v53, 0, v53
	v_fmamk_f32 v168, v168, 0x3a800000, v1
	global_store_dwordx4 v[62:63], v[58:61], off
	v_pk_mul_f32 v[56:57], v[56:57], v[56:57]
	v_pk_mul_f32 v[54:55], v[54:55], v[54:55]
	v_pk_mul_f32 v[58:59], v[52:53], v[52:53]
	v_pk_mul_f32 v[52:53], v[50:51], v[50:51]
	v_pk_fma_f32 v[46:47], v[46:47], v[172:173], v[144:145] op_sel_hi:[1,0,1]
	v_rsq_f32_e32 v168, v168
	v_cvt_pk_bf16_f32 v50, v54, v55
	v_cvt_pk_bf16_f32 v51, v56, v57
	v_cvt_pk_bf16_f32 v52, v52, v53
	v_cvt_pk_bf16_f32 v53, v58, v59
	v_pk_fma_f32 v[48:49], v[48:49], v[172:173], v[146:147] op_sel_hi:[1,0,1]
	v_pk_fma_f32 v[44:45], v[44:45], v[172:173], v[142:143] op_sel_hi:[1,0,1]
	v_pk_fma_f32 v[42:43], v[42:43], v[172:173], v[140:141] op_sel_hi:[1,0,1]
	v_max_f32_e32 v46, 0, v46
	v_max_f32_e32 v47, 0, v47
	global_store_dwordx4 v[62:63], v[50:53], off offset:256
	v_max_f32_e32 v42, 0, v42
	v_max_f32_e32 v43, 0, v43
	v_lshlrev_b64 v[50:51], 13, v[164:165]
	v_max_f32_e32 v48, 0, v48
	v_max_f32_e32 v44, 0, v44
	v_max_f32_e32 v49, 0, v49
	v_max_f32_e32 v45, 0, v45
	v_pk_mul_f32 v[46:47], v[46:47], v[46:47]
	v_pk_mul_f32 v[48:49], v[48:49], v[48:49]
	v_pk_mul_f32 v[52:53], v[44:45], v[44:45]
	v_pk_mul_f32 v[44:45], v[42:43], v[42:43]
	v_cvt_pk_bf16_f32 v42, v46, v47
	v_lshl_add_u64 v[46:47], s[24:25], 0, v[50:51]
	v_pk_fma_f32 v[40:41], v[40:41], v[172:173], v[138:139] op_sel_hi:[1,0,1]
	v_pk_fma_f32 v[38:39], v[38:39], v[172:173], v[136:137] op_sel_hi:[1,0,1]
	v_pk_fma_f32 v[36:37], v[36:37], v[172:173], v[134:135] op_sel_hi:[1,0,1]
	v_pk_fma_f32 v[34:35], v[34:35], v[172:173], v[132:133] op_sel_hi:[1,0,1]
	v_cvt_pk_bf16_f32 v43, v48, v49
	v_cvt_pk_bf16_f32 v44, v44, v45
	v_cvt_pk_bf16_f32 v45, v52, v53
	v_lshl_add_u64 v[46:47], v[46:47], 0, v[162:163]
	v_max_f32_e32 v38, 0, v38
	v_max_f32_e32 v34, 0, v34
	v_max_f32_e32 v39, 0, v39
	v_max_f32_e32 v35, 0, v35
	v_max_f32_e32 v40, 0, v40
	v_max_f32_e32 v36, 0, v36
	v_max_f32_e32 v41, 0, v41
	v_max_f32_e32 v37, 0, v37
	v_fmamk_f32 v160, v160, 0x3a800000, v1
	global_store_dwordx4 v[46:47], v[42:45], off
	v_pk_mul_f32 v[40:41], v[40:41], v[40:41]
	v_pk_mul_f32 v[38:39], v[38:39], v[38:39]
	v_pk_mul_f32 v[42:43], v[36:37], v[36:37]
	v_pk_mul_f32 v[36:37], v[34:35], v[34:35]
	v_pk_fma_f32 v[30:31], v[30:31], v[168:169], v[144:145] op_sel_hi:[1,0,1]
	v_rsq_f32_e32 v160, v160
	v_cvt_pk_bf16_f32 v34, v38, v39
	v_cvt_pk_bf16_f32 v35, v40, v41
	v_cvt_pk_bf16_f32 v36, v36, v37
	v_cvt_pk_bf16_f32 v37, v42, v43
	v_pk_fma_f32 v[32:33], v[32:33], v[168:169], v[146:147] op_sel_hi:[1,0,1]
	v_pk_fma_f32 v[28:29], v[28:29], v[168:169], v[142:143] op_sel_hi:[1,0,1]
	v_pk_fma_f32 v[26:27], v[26:27], v[168:169], v[140:141] op_sel_hi:[1,0,1]
	v_max_f32_e32 v30, 0, v30
	v_max_f32_e32 v31, 0, v31
	global_store_dwordx4 v[46:47], v[34:37], off offset:256
	v_max_f32_e32 v26, 0, v26
	v_max_f32_e32 v27, 0, v27
	v_lshlrev_b64 v[34:35], 13, v[158:159]
	v_max_f32_e32 v32, 0, v32
	v_max_f32_e32 v28, 0, v28
	v_max_f32_e32 v33, 0, v33
	v_max_f32_e32 v29, 0, v29
	v_pk_mul_f32 v[30:31], v[30:31], v[30:31]
	v_pk_mul_f32 v[32:33], v[32:33], v[32:33]
	v_pk_mul_f32 v[36:37], v[28:29], v[28:29]
	v_pk_mul_f32 v[28:29], v[26:27], v[26:27]
	v_cvt_pk_bf16_f32 v26, v30, v31
	v_lshl_add_u64 v[30:31], s[24:25], 0, v[34:35]
	v_pk_fma_f32 v[24:25], v[24:25], v[168:169], v[138:139] op_sel_hi:[1,0,1]
	v_pk_fma_f32 v[22:23], v[22:23], v[168:169], v[136:137] op_sel_hi:[1,0,1]
	v_pk_fma_f32 v[20:21], v[20:21], v[168:169], v[134:135] op_sel_hi:[1,0,1]
	v_pk_fma_f32 v[18:19], v[18:19], v[168:169], v[132:133] op_sel_hi:[1,0,1]
	v_cvt_pk_bf16_f32 v27, v32, v33
	v_cvt_pk_bf16_f32 v28, v28, v29
	v_cvt_pk_bf16_f32 v29, v36, v37
	v_lshl_add_u64 v[30:31], v[30:31], 0, v[162:163]
	v_max_f32_e32 v22, 0, v22
	v_max_f32_e32 v18, 0, v18
	v_max_f32_e32 v23, 0, v23
	v_max_f32_e32 v19, 0, v19
	v_max_f32_e32 v24, 0, v24
	v_max_f32_e32 v20, 0, v20
	v_max_f32_e32 v25, 0, v25
	v_max_f32_e32 v21, 0, v21
	global_store_dwordx4 v[30:31], v[26:29], off
	v_pk_mul_f32 v[24:25], v[24:25], v[24:25]
	v_pk_mul_f32 v[22:23], v[22:23], v[22:23]
	v_pk_mul_f32 v[26:27], v[20:21], v[20:21]
	v_pk_mul_f32 v[20:21], v[18:19], v[18:19]
	v_pk_fma_f32 v[14:15], v[14:15], v[160:161], v[144:145] op_sel_hi:[1,0,1]
	v_cvt_pk_bf16_f32 v18, v22, v23
	v_cvt_pk_bf16_f32 v19, v24, v25
	v_cvt_pk_bf16_f32 v20, v20, v21
	v_cvt_pk_bf16_f32 v21, v26, v27
	v_pk_fma_f32 v[16:17], v[16:17], v[160:161], v[146:147] op_sel_hi:[1,0,1]
	v_pk_fma_f32 v[12:13], v[12:13], v[160:161], v[142:143] op_sel_hi:[1,0,1]
	v_pk_fma_f32 v[10:11], v[10:11], v[160:161], v[140:141] op_sel_hi:[1,0,1]
	v_max_f32_e32 v14, 0, v14
	v_max_f32_e32 v15, 0, v15
	global_store_dwordx4 v[30:31], v[18:21], off offset:256
	v_max_f32_e32 v10, 0, v10
	v_max_f32_e32 v11, 0, v11
	v_lshlrev_b64 v[18:19], 13, v[156:157]
	v_max_f32_e32 v16, 0, v16
	v_max_f32_e32 v12, 0, v12
	v_max_f32_e32 v17, 0, v17
	v_max_f32_e32 v13, 0, v13
	v_pk_mul_f32 v[14:15], v[14:15], v[14:15]
	v_pk_mul_f32 v[16:17], v[16:17], v[16:17]
	v_pk_mul_f32 v[20:21], v[12:13], v[12:13]
	v_pk_mul_f32 v[12:13], v[10:11], v[10:11]
	v_cvt_pk_bf16_f32 v10, v14, v15
	v_lshl_add_u64 v[14:15], s[24:25], 0, v[18:19]
	v_pk_fma_f32 v[8:9], v[8:9], v[160:161], v[138:139] op_sel_hi:[1,0,1]
	v_pk_fma_f32 v[6:7], v[6:7], v[160:161], v[136:137] op_sel_hi:[1,0,1]
	v_pk_fma_f32 v[4:5], v[4:5], v[160:161], v[134:135] op_sel_hi:[1,0,1]
	v_pk_fma_f32 v[2:3], v[2:3], v[160:161], v[132:133] op_sel_hi:[1,0,1]
	v_cvt_pk_bf16_f32 v11, v16, v17
	v_cvt_pk_bf16_f32 v12, v12, v13
	v_cvt_pk_bf16_f32 v13, v20, v21
	v_lshl_add_u64 v[14:15], v[14:15], 0, v[162:163]
	v_max_f32_e32 v6, 0, v6
	v_max_f32_e32 v2, 0, v2
	v_max_f32_e32 v7, 0, v7
	v_max_f32_e32 v3, 0, v3
	v_max_f32_e32 v8, 0, v8
	v_max_f32_e32 v4, 0, v4
	v_max_f32_e32 v9, 0, v9
	v_max_f32_e32 v5, 0, v5
	global_store_dwordx4 v[14:15], v[10:13], off
	v_pk_mul_f32 v[8:9], v[8:9], v[8:9]
	v_pk_mul_f32 v[6:7], v[6:7], v[6:7]
	v_pk_mul_f32 v[10:11], v[4:5], v[4:5]
	v_pk_mul_f32 v[4:5], v[2:3], v[2:3]
	v_cvt_pk_bf16_f32 v2, v6, v7
	v_cvt_pk_bf16_f32 v3, v8, v9
	v_cvt_pk_bf16_f32 v4, v4, v5
	v_cvt_pk_bf16_f32 v5, v10, v11
	global_store_dwordx4 v[14:15], v[2:5], off offset:256
	s_cbranch_vccnz .LBB0_1003
	s_andn2_b64 vcc, exec, s[10:11]
	s_cbranch_vccnz .LBB0_1002
	s_barrier
	s_branch .LBB0_1002
